# attention prompt p_k/p_v output tail: 16 serial load-wait-store iterations unrolled with all loads in flight
# baseline (speedup 1.0000x reference)
.LBB0_572:
	v_ashrrev_i32_e32 v3, 6, v2
	v_mov_b64_e32 v[6:7], s[88:89]
	v_add_u32_e32 v8, s6, v3
	s_lshl_b32 s96, s72, 1
	v_mad_i64_i32 v[6:7], s[8:9], v8, s66, v[6:7]
	v_lshl_add_u64 v[6:7], v[6:7], 0, s[96:97]
	v_lshl_add_u64 v[6:7], v[6:7], 0, v[0:1]
	v_add_co_u32_e32 v6, vcc, 0x3000, v6
	s_nop 1
	v_addc_co_u32_e32 v7, vcc, 0, v7, vcc
	v_add_u32_e32 v146, s7, v3
	v_ashrrev_i32_e32 v147, 31, v146
	v_lshlrev_b64 v[146:147], 10, v[146:147]
	v_lshl_add_u64 v[146:147], v[4:5], 0, v[146:147]
	v_add_co_u32_e32 v146, vcc, 0x4668000, v146
	s_nop 1
	v_addc_co_u32_e32 v147, vcc, 0, v147, vcc
	global_load_ushort v182, v[6:7], off offset:1056
	global_load_ushort v183, v[6:7], off offset:1568
	v_add_co_u32_e32 v6, vcc, 0x35000, v6
	s_nop 1
	v_addc_co_u32_e32 v7, vcc, 0, v7, vcc
	global_load_ushort v184, v[6:7], off offset:1056
	global_load_ushort v185, v[6:7], off offset:1568
	v_add_co_u32_e32 v6, vcc, 0x35000, v6
	s_nop 1
	v_addc_co_u32_e32 v7, vcc, 0, v7, vcc
	global_load_ushort v186, v[6:7], off offset:1056
	global_load_ushort v187, v[6:7], off offset:1568
	v_add_co_u32_e32 v6, vcc, 0x35000, v6
	s_nop 1
	v_addc_co_u32_e32 v7, vcc, 0, v7, vcc
	global_load_ushort v188, v[6:7], off offset:1056
	global_load_ushort v189, v[6:7], off offset:1568
	v_add_co_u32_e32 v6, vcc, 0x35000, v6
	s_nop 1
	v_addc_co_u32_e32 v7, vcc, 0, v7, vcc
	global_load_ushort v190, v[6:7], off offset:1056
	global_load_ushort v191, v[6:7], off offset:1568
	v_add_co_u32_e32 v6, vcc, 0x35000, v6
	s_nop 1
	v_addc_co_u32_e32 v7, vcc, 0, v7, vcc
	global_load_ushort v192, v[6:7], off offset:1056
	global_load_ushort v193, v[6:7], off offset:1568
	v_add_co_u32_e32 v6, vcc, 0x35000, v6
	s_nop 1
	v_addc_co_u32_e32 v7, vcc, 0, v7, vcc
	global_load_ushort v194, v[6:7], off offset:1056
	global_load_ushort v195, v[6:7], off offset:1568
	v_add_co_u32_e32 v6, vcc, 0x35000, v6
	s_nop 1
	v_addc_co_u32_e32 v7, vcc, 0, v7, vcc
	global_load_ushort v196, v[6:7], off offset:1056
	global_load_ushort v197, v[6:7], off offset:1568
	v_add_co_u32_e32 v6, vcc, 0x35000, v6
	s_nop 1
	v_addc_co_u32_e32 v7, vcc, 0, v7, vcc
	global_load_ushort v198, v[6:7], off offset:1056
	global_load_ushort v199, v[6:7], off offset:1568
	v_add_co_u32_e32 v6, vcc, 0x35000, v6
	s_nop 1
	v_addc_co_u32_e32 v7, vcc, 0, v7, vcc
	global_load_ushort v200, v[6:7], off offset:1056
	global_load_ushort v201, v[6:7], off offset:1568
	v_add_co_u32_e32 v6, vcc, 0x35000, v6
	s_nop 1
	v_addc_co_u32_e32 v7, vcc, 0, v7, vcc
	global_load_ushort v202, v[6:7], off offset:1056
	global_load_ushort v203, v[6:7], off offset:1568
	v_add_co_u32_e32 v6, vcc, 0x35000, v6
	s_nop 1
	v_addc_co_u32_e32 v7, vcc, 0, v7, vcc
	global_load_ushort v204, v[6:7], off offset:1056
	global_load_ushort v205, v[6:7], off offset:1568
	v_add_co_u32_e32 v6, vcc, 0x35000, v6
	s_nop 1
	v_addc_co_u32_e32 v7, vcc, 0, v7, vcc
	global_load_ushort v206, v[6:7], off offset:1056
	global_load_ushort v207, v[6:7], off offset:1568
	v_add_co_u32_e32 v6, vcc, 0x35000, v6
	s_nop 1
	v_addc_co_u32_e32 v7, vcc, 0, v7, vcc
	global_load_ushort v208, v[6:7], off offset:1056
	global_load_ushort v209, v[6:7], off offset:1568
	v_add_co_u32_e32 v6, vcc, 0x35000, v6
	s_nop 1
	v_addc_co_u32_e32 v7, vcc, 0, v7, vcc
	global_load_ushort v210, v[6:7], off offset:1056
	global_load_ushort v211, v[6:7], off offset:1568
	v_add_co_u32_e32 v6, vcc, 0x35000, v6
	s_nop 1
	v_addc_co_u32_e32 v7, vcc, 0, v7, vcc
	global_load_ushort v212, v[6:7], off offset:1056
	global_load_ushort v213, v[6:7], off offset:1568
	s_waitcnt vmcnt(0)
	v_lshlrev_b32_e32 v182, 16, v182
	v_lshlrev_b32_e32 v183, 16, v183
	v_add_co_u32_e32 v148, vcc, 0x200000, v146
	s_nop 1
	v_addc_co_u32_e32 v149, vcc, 0, v147, vcc
	global_store_dword v[146:147], v182, off
	global_store_dword v[148:149], v183, off
	v_add_co_u32_e32 v146, vcc, 0x2000, v146
	s_nop 1
	v_addc_co_u32_e32 v147, vcc, 0, v147, vcc
	v_lshlrev_b32_e32 v184, 16, v184
	v_lshlrev_b32_e32 v185, 16, v185
	v_add_co_u32_e32 v148, vcc, 0x200000, v146
	s_nop 1
	v_addc_co_u32_e32 v149, vcc, 0, v147, vcc
	global_store_dword v[146:147], v184, off
	global_store_dword v[148:149], v185, off
	v_add_co_u32_e32 v146, vcc, 0x2000, v146
	s_nop 1
	v_addc_co_u32_e32 v147, vcc, 0, v147, vcc
	v_lshlrev_b32_e32 v186, 16, v186
	v_lshlrev_b32_e32 v187, 16, v187
	v_add_co_u32_e32 v148, vcc, 0x200000, v146
	s_nop 1
	v_addc_co_u32_e32 v149, vcc, 0, v147, vcc
	global_store_dword v[146:147], v186, off
	global_store_dword v[148:149], v187, off
	v_add_co_u32_e32 v146, vcc, 0x2000, v146
	s_nop 1
	v_addc_co_u32_e32 v147, vcc, 0, v147, vcc
	v_lshlrev_b32_e32 v188, 16, v188
	v_lshlrev_b32_e32 v189, 16, v189
	v_add_co_u32_e32 v148, vcc, 0x200000, v146
	s_nop 1
	v_addc_co_u32_e32 v149, vcc, 0, v147, vcc
	global_store_dword v[146:147], v188, off
	global_store_dword v[148:149], v189, off
	v_add_co_u32_e32 v146, vcc, 0x2000, v146
	s_nop 1
	v_addc_co_u32_e32 v147, vcc, 0, v147, vcc
	v_lshlrev_b32_e32 v190, 16, v190
	v_lshlrev_b32_e32 v191, 16, v191
	v_add_co_u32_e32 v148, vcc, 0x200000, v146
	s_nop 1
	v_addc_co_u32_e32 v149, vcc, 0, v147, vcc
	global_store_dword v[146:147], v190, off
	global_store_dword v[148:149], v191, off
	v_add_co_u32_e32 v146, vcc, 0x2000, v146
	s_nop 1
	v_addc_co_u32_e32 v147, vcc, 0, v147, vcc
	v_lshlrev_b32_e32 v192, 16, v192
	v_lshlrev_b32_e32 v193, 16, v193
	v_add_co_u32_e32 v148, vcc, 0x200000, v146
	s_nop 1
	v_addc_co_u32_e32 v149, vcc, 0, v147, vcc
	global_store_dword v[146:147], v192, off
	global_store_dword v[148:149], v193, off
	v_add_co_u32_e32 v146, vcc, 0x2000, v146
	s_nop 1
	v_addc_co_u32_e32 v147, vcc, 0, v147, vcc
	v_lshlrev_b32_e32 v194, 16, v194
	v_lshlrev_b32_e32 v195, 16, v195
	v_add_co_u32_e32 v148, vcc, 0x200000, v146
	s_nop 1
	v_addc_co_u32_e32 v149, vcc, 0, v147, vcc
	global_store_dword v[146:147], v194, off
	global_store_dword v[148:149], v195, off
	v_add_co_u32_e32 v146, vcc, 0x2000, v146
	s_nop 1
	v_addc_co_u32_e32 v147, vcc, 0, v147, vcc
	v_lshlrev_b32_e32 v196, 16, v196
	v_lshlrev_b32_e32 v197, 16, v197
	v_add_co_u32_e32 v148, vcc, 0x200000, v146
	s_nop 1
	v_addc_co_u32_e32 v149, vcc, 0, v147, vcc
	global_store_dword v[146:147], v196, off
	global_store_dword v[148:149], v197, off
	v_add_co_u32_e32 v146, vcc, 0x2000, v146
	s_nop 1
	v_addc_co_u32_e32 v147, vcc, 0, v147, vcc
	v_lshlrev_b32_e32 v198, 16, v198
	v_lshlrev_b32_e32 v199, 16, v199
	v_add_co_u32_e32 v148, vcc, 0x200000, v146
	s_nop 1
	v_addc_co_u32_e32 v149, vcc, 0, v147, vcc
	global_store_dword v[146:147], v198, off
	global_store_dword v[148:149], v199, off
	v_add_co_u32_e32 v146, vcc, 0x2000, v146
	s_nop 1
	v_addc_co_u32_e32 v147, vcc, 0, v147, vcc
	v_lshlrev_b32_e32 v200, 16, v200
	v_lshlrev_b32_e32 v201, 16, v201
	v_add_co_u32_e32 v148, vcc, 0x200000, v146
	s_nop 1
	v_addc_co_u32_e32 v149, vcc, 0, v147, vcc
	global_store_dword v[146:147], v200, off
	global_store_dword v[148:149], v201, off
	v_add_co_u32_e32 v146, vcc, 0x2000, v146
	s_nop 1
	v_addc_co_u32_e32 v147, vcc, 0, v147, vcc
	v_lshlrev_b32_e32 v202, 16, v202
	v_lshlrev_b32_e32 v203, 16, v203
	v_add_co_u32_e32 v148, vcc, 0x200000, v146
	s_nop 1
	v_addc_co_u32_e32 v149, vcc, 0, v147, vcc
	global_store_dword v[146:147], v202, off
	global_store_dword v[148:149], v203, off
	v_add_co_u32_e32 v146, vcc, 0x2000, v146
	s_nop 1
	v_addc_co_u32_e32 v147, vcc, 0, v147, vcc
	v_lshlrev_b32_e32 v204, 16, v204
	v_lshlrev_b32_e32 v205, 16, v205
	v_add_co_u32_e32 v148, vcc, 0x200000, v146
	s_nop 1
	v_addc_co_u32_e32 v149, vcc, 0, v147, vcc
	global_store_dword v[146:147], v204, off
	global_store_dword v[148:149], v205, off
	v_add_co_u32_e32 v146, vcc, 0x2000, v146
	s_nop 1
	v_addc_co_u32_e32 v147, vcc, 0, v147, vcc
	v_lshlrev_b32_e32 v206, 16, v206
	v_lshlrev_b32_e32 v207, 16, v207
	v_add_co_u32_e32 v148, vcc, 0x200000, v146
	s_nop 1
	v_addc_co_u32_e32 v149, vcc, 0, v147, vcc
	global_store_dword v[146:147], v206, off
	global_store_dword v[148:149], v207, off
	v_add_co_u32_e32 v146, vcc, 0x2000, v146
	s_nop 1
	v_addc_co_u32_e32 v147, vcc, 0, v147, vcc
	v_lshlrev_b32_e32 v208, 16, v208
	v_lshlrev_b32_e32 v209, 16, v209
	v_add_co_u32_e32 v148, vcc, 0x200000, v146
	s_nop 1
	v_addc_co_u32_e32 v149, vcc, 0, v147, vcc
	global_store_dword v[146:147], v208, off
	global_store_dword v[148:149], v209, off
	v_add_co_u32_e32 v146, vcc, 0x2000, v146
	s_nop 1
	v_addc_co_u32_e32 v147, vcc, 0, v147, vcc
	v_lshlrev_b32_e32 v210, 16, v210
	v_lshlrev_b32_e32 v211, 16, v211
	v_add_co_u32_e32 v148, vcc, 0x200000, v146
	s_nop 1
	v_addc_co_u32_e32 v149, vcc, 0, v147, vcc
	global_store_dword v[146:147], v210, off
	global_store_dword v[148:149], v211, off
	v_add_co_u32_e32 v146, vcc, 0x2000, v146
	s_nop 1
	v_addc_co_u32_e32 v147, vcc, 0, v147, vcc
	v_lshlrev_b32_e32 v212, 16, v212
	v_lshlrev_b32_e32 v213, 16, v213
	v_add_co_u32_e32 v148, vcc, 0x200000, v146
	s_nop 1
	v_addc_co_u32_e32 v149, vcc, 0, v147, vcc
	global_store_dword v[146:147], v212, off
	global_store_dword v[148:149], v213, off
